# mixer attention tasks (MLA and SWA): one static s_setprio 1 for the waves of the second half-block, reset at task end
# speedup vs baseline: 1.0032x; 1.0032x over previous
; #define VHALF ((int)__builtin_amdgcn_readfirstlane((int)(threadIdx.x >> 8)))
; DI void mixer_phase(const Params& p, int layer, char* lds, char* lds_all, int* s_tile) {
;     ...
;   for (;;) {
;     __syncthreads();
;     if (threadIdx.x == 0) *s_tile = atomicAdd(cnt, 1);
;     __syncthreads();
;     const int t = 2 * (*s_tile) + VHALF;
.LBB0_401:
	s_setprio 0
	s_mov_b32 s58, 0x800000
	s_movk_i32 s47, 0x1000
	s_mov_b64 s[0:1], 0
	v_readlane_b32 s8, v252, 26

; DI void mixer_phase(const Params& p, int layer, char* lds, char* lds_all, int* s_tile) {
;     ...
;     else if (t < 256 + nattn) mla_attn(p, t - 256, lds_all);
;     else if (t < nwork) swa_attn(p, layer, t - 256 - nattn, lds_all);
.LBB0_551:
	s_bitcmp1_b32 s38, 8
	s_cbranch_scc0 .Lprio_skip_b
	s_setprio 1
